# window conversion reduced to 4096 items per layer (4 per idle wave) to fit the mix-in tail round
# baseline (speedup 1.0000x reference)
.LBB0_10:
	s_movk_i32 s0, 0x1680
	v_writelane_b32 v247, s0, 0
	s_movk_i32 s0, 0x1000
	s_nop 0
	v_writelane_b32 v247, s0, 8
	s_movk_i32 s0, 0x1400
	s_nop 0
	v_writelane_b32 v247, s0, 9
	s_mov_b32 s0, 0
	s_nop 1
	v_writelane_b32 v247, s0, 1
	s_nop 1
	v_writelane_b32 v247, s0, 3
	s_nop 1
	v_writelane_b32 v247, s0, 6
	s_movk_i32 s0, 0xb00
	s_nop 0
	v_writelane_b32 v247, s0, 2
	s_movk_i32 s0, 0x2d00
	s_nop 0
	v_writelane_b32 v247, s0, 5
	s_waitcnt lgkmcnt(0)
	s_lshl_b32 s0, s66, 3
	s_nop 0
	v_writelane_b32 v247, s0, 4
	s_lshr_b32 s100, s2, 6
	s_lshl_b32 s0, s74, 3
	s_add_i32 s100, s100, s0

.LBB0_14:
	v_readlane_b32 s2, v247, 0
	v_readlane_b32 s4, v247, 1
	v_readlane_b32 s5, v247, 2
	v_readlane_b32 s42, v247, 3
	s_nop 0
	s_cmp_ge_i32 s100, s2
	s_cselect_b32 s43, 1, 0
	s_cselect_b32 s2, s2, 0
	s_sub_i32 s2, s100, s2
	v_readlane_b32 s41, v247, 9
	v_readlane_b32 s40, v247, 8
	s_nop 0
	s_cmp_lt_i32 s2, s41
	s_cselect_b32 s5, s5, s40
	s_cmpk_lt_i32 s2, 0xb00
	s_cselect_b32 s4, s4, s5
	s_add_i32 s2, s2, s4
	s_add_i32 s42, s42, s43
	s_mulk_i32 s42, 0x2680
	s_add_i32 s69, s2, s42
	s_lshl_b32 s46, s69, 7
	s_mul_hi_i32 s2, s69, 0x3531dec1
	s_lshr_b32 s4, s2, 31
	s_ashr_i32 s2, s2, 11
	s_add_i32 s42, s2, s4
	s_mul_i32 s2, s42, 0xffffd980
	s_add_i32 s70, s69, s2
	s_ashr_i32 s43, s42, 31
	s_mul_i32 s4, s42, 0x9a00000
	s_mul_hi_i32 s2, s42, 0x9a00000
	s_add_u32 s40, s3, s4
	s_addc_u32 s41, s33, s2
	s_cmpk_gt_i32 s70, 0xaff
	s_mov_b64 s[4:5], -1
	s_cbranch_scc0 .LBB0_96
	s_cmpk_gt_u32 s70, 0x15ff
	s_cbranch_scc0 .LBB0_61
	s_cmpk_gt_u32 s70, 0x197f
	s_cbranch_scc0 .LBB0_26
	s_cmpk_gt_u32 s70, 0x1eff
	s_cbranch_scc0 .LBB0_23
	s_and_b32 s44, s46, 0x780
	s_cmpk_gt_u32 s70, 0x247f
	s_cbranch_scc0 .LBB0_20
	s_lshl_b64 s[4:5], s[42:43], 24
	s_add_u32 s4, s16, s4
	s_addc_u32 s5, s17, s5
	s_add_i32 s2, s70, 0xdb80
	s_bfe_u32 s2, s2, 0xc0004
	v_lshlrev_b32_e32 v2, 2, v135
	v_lshl_or_b32 v132, s2, 19, v2
	v_lshl_add_u64 v[2:3], s[4:5], 0, v[132:133]
	s_lshl_b32 s38, s44, 2
	v_lshl_add_u64 v[2:3], v[2:3], 0, s[38:39]
	v_lshlrev_b32_e32 v132, 2, v130
	v_lshl_add_u64 v[2:3], v[2:3], 0, v[132:133]
	v_add_co_u32_e32 v4, vcc, s68, v2
	s_mov_b32 s4, 0x8000
	s_nop 0
	v_addc_co_u32_e32 v5, vcc, 0, v3, vcc
	global_load_dwordx4 v[106:109], v[2:3], off
	global_load_dwordx4 v[110:113], v[4:5], off
	v_add_co_u32_e32 v4, vcc, s4, v2
	s_mov_b32 s4, 0xa000
	s_nop 0
	v_addc_co_u32_e32 v5, vcc, 0, v3, vcc
	v_add_co_u32_e32 v6, vcc, s4, v2
	s_mov_b32 s4, 0x10000
	s_nop 0
	v_addc_co_u32_e32 v7, vcc, 0, v3, vcc
	global_load_dwordx4 v[114:117], v[4:5], off
	global_load_dwordx4 v[118:121], v[6:7], off
	v_add_co_u32_e32 v4, vcc, s4, v2
	s_mov_b32 s4, 0x12000
	s_nop 0
	v_addc_co_u32_e32 v5, vcc, 0, v3, vcc
	v_add_co_u32_e32 v6, vcc, s4, v2
	s_mov_b32 s4, 0x18000
	s_nop 0
	v_addc_co_u32_e32 v7, vcc, 0, v3, vcc
	global_load_dwordx4 v[122:125], v[4:5], off
	global_load_dwordx4 v[126:129], v[6:7], off
	v_add_co_u32_e32 v4, vcc, s4, v2
	s_mov_b32 s4, 0x1a000
	s_nop 0
	v_addc_co_u32_e32 v5, vcc, 0, v3, vcc
	v_add_co_u32_e32 v6, vcc, s4, v2
	s_mov_b32 s4, 0x20000
	s_nop 0
	v_addc_co_u32_e32 v7, vcc, 0, v3, vcc
	global_load_dwordx4 v[98:101], v[4:5], off
	global_load_dwordx4 v[102:105], v[6:7], off
	v_add_co_u32_e32 v4, vcc, s4, v2
	s_mov_b32 s4, 0x22000
	s_nop 0
	v_addc_co_u32_e32 v5, vcc, 0, v3, vcc
	v_add_co_u32_e32 v6, vcc, s4, v2
	s_mov_b32 s4, 0x28000
	s_nop 0
	v_addc_co_u32_e32 v7, vcc, 0, v3, vcc
	global_load_dwordx4 v[90:93], v[4:5], off
	global_load_dwordx4 v[94:97], v[6:7], off
	v_add_co_u32_e32 v4, vcc, s4, v2
	s_mov_b32 s4, 0x30000
	s_nop 0
	v_addc_co_u32_e32 v5, vcc, 0, v3, vcc
	v_add_co_u32_e32 v6, vcc, s58, v2
	s_lshl_b32 s2, s2, 11
	s_nop 0
	v_addc_co_u32_e32 v7, vcc, 0, v3, vcc
	global_load_dwordx4 v[82:85], v[4:5], off
	global_load_dwordx4 v[86:89], v[6:7], off
	v_add_co_u32_e32 v4, vcc, s4, v2
	s_mov_b32 s4, 0x32000
	s_nop 0
	v_addc_co_u32_e32 v5, vcc, 0, v3, vcc
	v_add_co_u32_e32 v6, vcc, s4, v2
	s_mov_b32 s4, 0x3a000
	s_nop 0
	v_addc_co_u32_e32 v7, vcc, 0, v3, vcc
	global_load_dwordx4 v[74:77], v[4:5], off
	global_load_dwordx4 v[78:81], v[6:7], off
	v_add_co_u32_e32 v4, vcc, s61, v2
	s_waitcnt vmcnt(13)
	v_bfe_u32 v132, v106, 17, 1
	v_addc_co_u32_e32 v5, vcc, 0, v3, vcc
	v_add_co_u32_e32 v6, vcc, s4, v2
	s_mov_b32 s4, 0x40000
	s_nop 0
	v_addc_co_u32_e32 v7, vcc, 0, v3, vcc
	global_load_dwordx4 v[66:69], v[4:5], off
	global_load_dwordx4 v[70:73], v[6:7], off
	v_add_co_u32_e32 v4, vcc, s4, v2
	s_mov_b32 s4, 0x42000
	s_nop 0
	v_addc_co_u32_e32 v5, vcc, 0, v3, vcc
	v_add_co_u32_e32 v6, vcc, s4, v2
	s_mov_b32 s4, 0x48000
	s_nop 0
	v_addc_co_u32_e32 v7, vcc, 0, v3, vcc
	global_load_dwordx4 v[58:61], v[4:5], off
	global_load_dwordx4 v[62:65], v[6:7], off
	v_add_co_u32_e32 v4, vcc, s4, v2
	s_mov_b32 s4, 0x4a000
	s_nop 0
	v_addc_co_u32_e32 v5, vcc, 0, v3, vcc
	v_add_co_u32_e32 v6, vcc, s4, v2
	s_mov_b32 s4, 0x50000
	s_nop 0
	v_addc_co_u32_e32 v7, vcc, 0, v3, vcc
	global_load_dwordx4 v[50:53], v[4:5], off
	global_load_dwordx4 v[54:57], v[6:7], off
	v_add_co_u32_e32 v4, vcc, s4, v2
	v_add3_u32 v106, v106, v132, s86
	s_nop 0
	v_addc_co_u32_e32 v5, vcc, 0, v3, vcc
	v_add_co_u32_e32 v6, vcc, s75, v2
	s_waitcnt vmcnt(18)
	v_bfe_u32 v132, v110, 17, 1
	v_addc_co_u32_e32 v7, vcc, 0, v3, vcc
	global_load_dwordx4 v[42:45], v[4:5], off
	global_load_dwordx4 v[46:49], v[6:7], off
	v_add_co_u32_e32 v4, vcc, s76, v2
	v_add3_u32 v110, v110, v132, s86
	s_nop 0
	v_addc_co_u32_e32 v5, vcc, 0, v3, vcc
	v_add_co_u32_e32 v6, vcc, s77, v2
	v_and_b32_e32 v106, 0xfffe0000, v106
	s_nop 0
	v_addc_co_u32_e32 v7, vcc, 0, v3, vcc
	global_load_dwordx4 v[34:37], v[4:5], off
	global_load_dwordx4 v[38:41], v[6:7], off
	v_add_co_u32_e32 v4, vcc, s78, v2
	v_and_b32_e32 v110, 0xfffe0000, v110
	s_nop 0
	v_addc_co_u32_e32 v5, vcc, 0, v3, vcc
	v_add_co_u32_e32 v6, vcc, s79, v2
	v_lshlrev_b32_e32 v132, 1, v134
	s_nop 0
	v_addc_co_u32_e32 v7, vcc, 0, v3, vcc
	global_load_dwordx4 v[26:29], v[4:5], off
	global_load_dwordx4 v[30:33], v[6:7], off
	v_add_co_u32_e32 v4, vcc, s80, v2
	s_mov_b64 s[4:5], 0x5000000
	s_nop 0
	v_addc_co_u32_e32 v5, vcc, 0, v3, vcc
	v_add_co_u32_e32 v6, vcc, s81, v2
	s_nop 1
	v_addc_co_u32_e32 v7, vcc, 0, v3, vcc
	global_load_dwordx4 v[18:21], v[4:5], off
	global_load_dwordx4 v[22:25], v[6:7], off
	v_add_co_u32_e32 v4, vcc, s82, v2
	s_nop 1
	v_addc_co_u32_e32 v5, vcc, 0, v3, vcc
	v_add_co_u32_e32 v6, vcc, s83, v2
	s_nop 1
	v_addc_co_u32_e32 v7, vcc, 0, v3, vcc
	global_load_dwordx4 v[10:13], v[4:5], off
	global_load_dwordx4 v[14:17], v[6:7], off
	v_add_co_u32_e32 v4, vcc, s84, v2
	s_nop 1
	v_addc_co_u32_e32 v5, vcc, 0, v3, vcc
	v_add_co_u32_e32 v6, vcc, s85, v2
	s_nop 1
	v_addc_co_u32_e32 v7, vcc, 0, v3, vcc
	global_load_dwordx4 v[2:5], v[4:5], off
	s_nop 0
	global_load_dwordx4 v[6:9], v[6:7], off
	v_cvt_pk_bf16_f32 v106, v106, v110
	v_add_u32_e32 v110, v142, v143
	ds_write_b32 v110, v106
	v_bfe_u32 v106, v107, 17, 1
	v_add3_u32 v106, v107, v106, s86
	v_bfe_u32 v107, v111, 17, 1
	v_and_b32_e32 v106, 0xfffe0000, v106
	v_add3_u32 v107, v111, v107, s86
	v_and_b32_e32 v107, 0xfffe0000, v107
	v_cvt_pk_bf16_f32 v106, v106, v107
	ds_write_b32 v110, v106 offset:128
	v_bfe_u32 v106, v108, 17, 1
	v_add3_u32 v106, v108, v106, s86
	v_bfe_u32 v107, v112, 17, 1
	v_and_b32_e32 v106, 0xfffe0000, v106
	v_add3_u32 v107, v112, v107, s86
	v_and_b32_e32 v107, 0xfffe0000, v107
	v_cvt_pk_bf16_f32 v106, v106, v107
	ds_write_b32 v110, v106 offset:256
	v_bfe_u32 v106, v109, 17, 1
	v_add3_u32 v106, v109, v106, s86
	v_bfe_u32 v107, v113, 17, 1
	v_and_b32_e32 v106, 0xfffe0000, v106
	v_add3_u32 v107, v113, v107, s86
	v_and_b32_e32 v107, 0xfffe0000, v107
	v_cvt_pk_bf16_f32 v106, v106, v107
	ds_write_b32 v110, v106 offset:384
	s_waitcnt vmcnt(29)
	v_bfe_u32 v106, v114, 17, 1
	v_add3_u32 v106, v114, v106, s86
	s_waitcnt vmcnt(28)
	v_bfe_u32 v107, v118, 17, 1
	v_and_b32_e32 v106, 0xfffe0000, v106
	v_add3_u32 v107, v118, v107, s86
	v_and_b32_e32 v107, 0xfffe0000, v107
	v_cvt_pk_bf16_f32 v106, v106, v107
	ds_write_b32 v110, v106 offset:1032
	v_bfe_u32 v106, v115, 17, 1
	v_add3_u32 v106, v115, v106, s86
	v_bfe_u32 v107, v119, 17, 1
	v_and_b32_e32 v106, 0xfffe0000, v106
	v_add3_u32 v107, v119, v107, s86
	v_and_b32_e32 v107, 0xfffe0000, v107
	v_cvt_pk_bf16_f32 v106, v106, v107
	ds_write_b32 v110, v106 offset:1160
	v_bfe_u32 v106, v116, 17, 1
	v_add3_u32 v106, v116, v106, s86
	v_bfe_u32 v107, v120, 17, 1
	v_and_b32_e32 v106, 0xfffe0000, v106
	v_add3_u32 v107, v120, v107, s86
	v_and_b32_e32 v107, 0xfffe0000, v107
	v_cvt_pk_bf16_f32 v106, v106, v107
	ds_write_b32 v110, v106 offset:1288
	v_bfe_u32 v106, v117, 17, 1
	v_add3_u32 v106, v117, v106, s86
	v_bfe_u32 v107, v121, 17, 1
	v_and_b32_e32 v106, 0xfffe0000, v106
	v_add3_u32 v107, v121, v107, s86
	v_and_b32_e32 v107, 0xfffe0000, v107
	v_cvt_pk_bf16_f32 v106, v106, v107
	ds_write_b32 v110, v106 offset:1416
	s_waitcnt vmcnt(27)
	v_bfe_u32 v106, v122, 17, 1
	v_add3_u32 v106, v122, v106, s86
	s_waitcnt vmcnt(26)
	v_bfe_u32 v107, v126, 17, 1
	v_and_b32_e32 v106, 0xfffe0000, v106
	v_add3_u32 v107, v126, v107, s86
	v_and_b32_e32 v107, 0xfffe0000, v107
	v_cvt_pk_bf16_f32 v106, v106, v107
	ds_write_b32 v110, v106 offset:2064
	v_bfe_u32 v106, v123, 17, 1
	v_add3_u32 v106, v123, v106, s86
	v_bfe_u32 v107, v127, 17, 1
	v_and_b32_e32 v106, 0xfffe0000, v106
	v_add3_u32 v107, v127, v107, s86
	v_and_b32_e32 v107, 0xfffe0000, v107
	v_cvt_pk_bf16_f32 v106, v106, v107
	ds_write_b32 v110, v106 offset:2192
	v_bfe_u32 v106, v124, 17, 1
	v_add3_u32 v106, v124, v106, s86
	v_bfe_u32 v107, v128, 17, 1
	v_and_b32_e32 v106, 0xfffe0000, v106
	v_add3_u32 v107, v128, v107, s86
	v_and_b32_e32 v107, 0xfffe0000, v107
	v_cvt_pk_bf16_f32 v106, v106, v107
	ds_write_b32 v110, v106 offset:2320
	v_bfe_u32 v106, v125, 17, 1
	v_add3_u32 v106, v125, v106, s86
	v_bfe_u32 v107, v129, 17, 1
	v_and_b32_e32 v106, 0xfffe0000, v106
	v_add3_u32 v107, v129, v107, s86
	v_and_b32_e32 v107, 0xfffe0000, v107
	v_cvt_pk_bf16_f32 v106, v106, v107
	ds_write_b32 v110, v106 offset:2448
	s_waitcnt vmcnt(25)
	v_bfe_u32 v106, v98, 17, 1
	v_add3_u32 v98, v98, v106, s86
	s_waitcnt vmcnt(24)
	v_bfe_u32 v106, v102, 17, 1
	v_and_b32_e32 v98, 0xfffe0000, v98
	v_add3_u32 v102, v102, v106, s86
	v_and_b32_e32 v102, 0xfffe0000, v102
	v_cvt_pk_bf16_f32 v98, v98, v102
	ds_write_b32 v110, v98 offset:3096
	v_bfe_u32 v98, v99, 17, 1
	v_add3_u32 v98, v99, v98, s86
	v_bfe_u32 v99, v103, 17, 1
	v_and_b32_e32 v98, 0xfffe0000, v98
	v_add3_u32 v99, v103, v99, s86
	v_and_b32_e32 v99, 0xfffe0000, v99
	v_cvt_pk_bf16_f32 v98, v98, v99
	ds_write_b32 v110, v98 offset:3224
	v_bfe_u32 v98, v100, 17, 1
	v_add3_u32 v98, v100, v98, s86
	v_bfe_u32 v99, v104, 17, 1
	v_and_b32_e32 v98, 0xfffe0000, v98
	v_add3_u32 v99, v104, v99, s86
	v_and_b32_e32 v99, 0xfffe0000, v99
	v_cvt_pk_bf16_f32 v98, v98, v99
	ds_write_b32 v110, v98 offset:3352
	v_bfe_u32 v98, v101, 17, 1
	v_add3_u32 v98, v101, v98, s86
	v_bfe_u32 v99, v105, 17, 1
	v_and_b32_e32 v98, 0xfffe0000, v98
	v_add3_u32 v99, v105, v99, s86
	v_and_b32_e32 v99, 0xfffe0000, v99
	v_cvt_pk_bf16_f32 v98, v98, v99
	ds_write_b32 v110, v98 offset:3480
	s_waitcnt vmcnt(23)
	v_bfe_u32 v98, v90, 17, 1
	v_add3_u32 v90, v90, v98, s86
	s_waitcnt vmcnt(22)
	v_bfe_u32 v98, v94, 17, 1
	v_and_b32_e32 v90, 0xfffe0000, v90
	v_add3_u32 v94, v94, v98, s86
	v_and_b32_e32 v94, 0xfffe0000, v94
	v_cvt_pk_bf16_f32 v90, v90, v94
	ds_write_b32 v110, v90 offset:4128
	v_bfe_u32 v90, v91, 17, 1
	v_add3_u32 v90, v91, v90, s86
	v_bfe_u32 v91, v95, 17, 1
	v_and_b32_e32 v90, 0xfffe0000, v90
	v_add3_u32 v91, v95, v91, s86
	v_and_b32_e32 v91, 0xfffe0000, v91
	v_cvt_pk_bf16_f32 v90, v90, v91
	ds_write_b32 v110, v90 offset:4256
	v_bfe_u32 v90, v92, 17, 1
	v_add3_u32 v90, v92, v90, s86
	v_bfe_u32 v91, v96, 17, 1
	v_and_b32_e32 v90, 0xfffe0000, v90
	v_add3_u32 v91, v96, v91, s86
	v_and_b32_e32 v91, 0xfffe0000, v91
	v_cvt_pk_bf16_f32 v90, v90, v91
	ds_write_b32 v110, v90 offset:4384
	v_bfe_u32 v90, v93, 17, 1
	v_add3_u32 v90, v93, v90, s86
	v_bfe_u32 v91, v97, 17, 1
	v_and_b32_e32 v90, 0xfffe0000, v90
	v_add3_u32 v91, v97, v91, s86
	v_and_b32_e32 v91, 0xfffe0000, v91
	v_cvt_pk_bf16_f32 v90, v90, v91
	ds_write_b32 v110, v90 offset:4512
	s_waitcnt vmcnt(21)
	v_bfe_u32 v90, v82, 17, 1
	v_add3_u32 v82, v82, v90, s86
	s_waitcnt vmcnt(20)
	v_bfe_u32 v90, v86, 17, 1
	v_and_b32_e32 v82, 0xfffe0000, v82
	v_add3_u32 v86, v86, v90, s86
	v_and_b32_e32 v86, 0xfffe0000, v86
	v_cvt_pk_bf16_f32 v82, v82, v86
	ds_write_b32 v110, v82 offset:5160
	v_bfe_u32 v82, v83, 17, 1
	v_add3_u32 v82, v83, v82, s86
	v_bfe_u32 v83, v87, 17, 1
	v_and_b32_e32 v82, 0xfffe0000, v82
	v_add3_u32 v83, v87, v83, s86
	v_and_b32_e32 v83, 0xfffe0000, v83
	v_cvt_pk_bf16_f32 v82, v82, v83
	ds_write_b32 v110, v82 offset:5288
	v_bfe_u32 v82, v84, 17, 1
	v_add3_u32 v82, v84, v82, s86
	v_bfe_u32 v83, v88, 17, 1
	v_and_b32_e32 v82, 0xfffe0000, v82
	v_add3_u32 v83, v88, v83, s86
	v_and_b32_e32 v83, 0xfffe0000, v83
	v_cvt_pk_bf16_f32 v82, v82, v83
	ds_write_b32 v110, v82 offset:5416
	v_bfe_u32 v82, v85, 17, 1
	v_add3_u32 v82, v85, v82, s86
	v_bfe_u32 v83, v89, 17, 1
	v_and_b32_e32 v82, 0xfffe0000, v82
	v_add3_u32 v83, v89, v83, s86
	v_and_b32_e32 v83, 0xfffe0000, v83
	v_cvt_pk_bf16_f32 v82, v82, v83
	ds_write_b32 v110, v82 offset:5544
	s_waitcnt vmcnt(19)
	v_bfe_u32 v82, v74, 17, 1
	v_add3_u32 v74, v74, v82, s86
	s_waitcnt vmcnt(18)
	v_bfe_u32 v82, v78, 17, 1
	v_and_b32_e32 v74, 0xfffe0000, v74
	v_add3_u32 v78, v78, v82, s86
	v_and_b32_e32 v78, 0xfffe0000, v78
	v_cvt_pk_bf16_f32 v74, v74, v78
	ds_write_b32 v110, v74 offset:6192
	v_bfe_u32 v74, v75, 17, 1
	v_add3_u32 v74, v75, v74, s86
	v_bfe_u32 v75, v79, 17, 1
	v_and_b32_e32 v74, 0xfffe0000, v74
	v_add3_u32 v75, v79, v75, s86
	v_and_b32_e32 v75, 0xfffe0000, v75
	v_cvt_pk_bf16_f32 v74, v74, v75
	ds_write_b32 v110, v74 offset:6320
	v_bfe_u32 v74, v76, 17, 1
	v_add3_u32 v74, v76, v74, s86
	v_bfe_u32 v75, v80, 17, 1
	v_and_b32_e32 v74, 0xfffe0000, v74
	v_add3_u32 v75, v80, v75, s86
	v_and_b32_e32 v75, 0xfffe0000, v75
	v_cvt_pk_bf16_f32 v74, v74, v75
	ds_write_b32 v110, v74 offset:6448
	v_bfe_u32 v74, v77, 17, 1
	v_add3_u32 v74, v77, v74, s86
	v_bfe_u32 v75, v81, 17, 1
	v_and_b32_e32 v74, 0xfffe0000, v74
	v_add3_u32 v75, v81, v75, s86
	v_and_b32_e32 v75, 0xfffe0000, v75
	v_cvt_pk_bf16_f32 v74, v74, v75
	ds_write_b32 v110, v74 offset:6576
	s_waitcnt vmcnt(17)
	v_bfe_u32 v74, v66, 17, 1
	v_add3_u32 v66, v66, v74, s86
	s_waitcnt vmcnt(16)
	v_bfe_u32 v74, v70, 17, 1
	v_and_b32_e32 v66, 0xfffe0000, v66
	v_add3_u32 v70, v70, v74, s86
	v_and_b32_e32 v70, 0xfffe0000, v70
	v_cvt_pk_bf16_f32 v66, v66, v70
	ds_write_b32 v110, v66 offset:7224
	v_bfe_u32 v66, v67, 17, 1
	v_add3_u32 v66, v67, v66, s86
	v_bfe_u32 v67, v71, 17, 1
	v_and_b32_e32 v66, 0xfffe0000, v66
	v_add3_u32 v67, v71, v67, s86
	v_and_b32_e32 v67, 0xfffe0000, v67
	v_cvt_pk_bf16_f32 v66, v66, v67
	ds_write_b32 v110, v66 offset:7352
	v_bfe_u32 v66, v68, 17, 1
	v_add3_u32 v66, v68, v66, s86
	v_bfe_u32 v67, v72, 17, 1
	v_and_b32_e32 v66, 0xfffe0000, v66
	v_add3_u32 v67, v72, v67, s86
	v_and_b32_e32 v67, 0xfffe0000, v67
	v_cvt_pk_bf16_f32 v66, v66, v67
	ds_write_b32 v110, v66 offset:7480
	v_bfe_u32 v66, v69, 17, 1
	v_add3_u32 v66, v69, v66, s86
	v_bfe_u32 v67, v73, 17, 1
	v_and_b32_e32 v66, 0xfffe0000, v66
	v_add3_u32 v67, v73, v67, s86
	v_and_b32_e32 v67, 0xfffe0000, v67
	v_cvt_pk_bf16_f32 v66, v66, v67
	ds_write_b32 v110, v66 offset:7608
	s_waitcnt vmcnt(15)
	v_bfe_u32 v66, v58, 17, 1
	v_add3_u32 v58, v58, v66, s86
	s_waitcnt vmcnt(14)
	v_bfe_u32 v66, v62, 17, 1
	v_and_b32_e32 v58, 0xfffe0000, v58
	v_add3_u32 v62, v62, v66, s86
	v_and_b32_e32 v62, 0xfffe0000, v62
	v_cvt_pk_bf16_f32 v58, v58, v62
	ds_write_b32 v110, v58 offset:8256
	v_bfe_u32 v58, v59, 17, 1
	v_add3_u32 v58, v59, v58, s86
	v_bfe_u32 v59, v63, 17, 1
	v_and_b32_e32 v58, 0xfffe0000, v58
	v_add3_u32 v59, v63, v59, s86
	v_and_b32_e32 v59, 0xfffe0000, v59
	v_cvt_pk_bf16_f32 v58, v58, v59
	ds_write_b32 v110, v58 offset:8384
	v_bfe_u32 v58, v60, 17, 1
	v_add3_u32 v58, v60, v58, s86
	v_bfe_u32 v59, v64, 17, 1
	v_and_b32_e32 v58, 0xfffe0000, v58
	v_add3_u32 v59, v64, v59, s86
	v_and_b32_e32 v59, 0xfffe0000, v59
	v_cvt_pk_bf16_f32 v58, v58, v59
	ds_write_b32 v110, v58 offset:8512
	v_bfe_u32 v58, v61, 17, 1
	v_add3_u32 v58, v61, v58, s86
	v_bfe_u32 v59, v65, 17, 1
	v_and_b32_e32 v58, 0xfffe0000, v58
	v_add3_u32 v59, v65, v59, s86
	v_and_b32_e32 v59, 0xfffe0000, v59
	v_cvt_pk_bf16_f32 v58, v58, v59
	ds_write_b32 v110, v58 offset:8640
	s_waitcnt vmcnt(13)
	v_bfe_u32 v58, v50, 17, 1
	v_add3_u32 v50, v50, v58, s86
	s_waitcnt vmcnt(12)
	v_bfe_u32 v58, v54, 17, 1
	v_and_b32_e32 v50, 0xfffe0000, v50
	v_add3_u32 v54, v54, v58, s86
	v_and_b32_e32 v54, 0xfffe0000, v54
	v_cvt_pk_bf16_f32 v50, v50, v54
	ds_write_b32 v110, v50 offset:9288
	v_bfe_u32 v50, v51, 17, 1
	v_add3_u32 v50, v51, v50, s86
	v_bfe_u32 v51, v55, 17, 1
	v_and_b32_e32 v50, 0xfffe0000, v50
	v_add3_u32 v51, v55, v51, s86
	v_and_b32_e32 v51, 0xfffe0000, v51
	v_cvt_pk_bf16_f32 v50, v50, v51
	ds_write_b32 v110, v50 offset:9416
	v_bfe_u32 v50, v52, 17, 1
	v_add3_u32 v50, v52, v50, s86
	v_bfe_u32 v51, v56, 17, 1
	v_and_b32_e32 v50, 0xfffe0000, v50
	v_add3_u32 v51, v56, v51, s86
	v_and_b32_e32 v51, 0xfffe0000, v51
	v_cvt_pk_bf16_f32 v50, v50, v51
	ds_write_b32 v110, v50 offset:9544
	v_bfe_u32 v50, v53, 17, 1
	v_add3_u32 v50, v53, v50, s86
	v_bfe_u32 v51, v57, 17, 1
	v_and_b32_e32 v50, 0xfffe0000, v50
	v_add3_u32 v51, v57, v51, s86
	v_and_b32_e32 v51, 0xfffe0000, v51
	v_cvt_pk_bf16_f32 v50, v50, v51
	ds_write_b32 v110, v50 offset:9672
	s_waitcnt vmcnt(11)
	v_bfe_u32 v50, v42, 17, 1
	v_add3_u32 v42, v42, v50, s86
	s_waitcnt vmcnt(10)
	v_bfe_u32 v50, v46, 17, 1
	v_and_b32_e32 v42, 0xfffe0000, v42
	v_add3_u32 v46, v46, v50, s86
	v_and_b32_e32 v46, 0xfffe0000, v46
	v_cvt_pk_bf16_f32 v42, v42, v46
	ds_write_b32 v110, v42 offset:10320
	v_bfe_u32 v42, v43, 17, 1
	v_add3_u32 v42, v43, v42, s86
	v_bfe_u32 v43, v47, 17, 1
	v_and_b32_e32 v42, 0xfffe0000, v42
	v_add3_u32 v43, v47, v43, s86
	v_and_b32_e32 v43, 0xfffe0000, v43
	v_cvt_pk_bf16_f32 v42, v42, v43
	ds_write_b32 v110, v42 offset:10448
	v_bfe_u32 v42, v44, 17, 1
	v_add3_u32 v42, v44, v42, s86
	v_bfe_u32 v43, v48, 17, 1
	v_and_b32_e32 v42, 0xfffe0000, v42
	v_add3_u32 v43, v48, v43, s86
	v_and_b32_e32 v43, 0xfffe0000, v43
	v_cvt_pk_bf16_f32 v42, v42, v43
	ds_write_b32 v110, v42 offset:10576
	v_bfe_u32 v42, v45, 17, 1
	v_add3_u32 v42, v45, v42, s86
	v_bfe_u32 v43, v49, 17, 1
	v_and_b32_e32 v42, 0xfffe0000, v42
	v_add3_u32 v43, v49, v43, s86
	v_and_b32_e32 v43, 0xfffe0000, v43
	v_cvt_pk_bf16_f32 v42, v42, v43
	ds_write_b32 v110, v42 offset:10704
	s_waitcnt vmcnt(9)
	v_bfe_u32 v42, v34, 17, 1
	v_add3_u32 v34, v34, v42, s86
	s_waitcnt vmcnt(8)
	v_bfe_u32 v42, v38, 17, 1
	v_and_b32_e32 v34, 0xfffe0000, v34
	v_add3_u32 v38, v38, v42, s86
	v_and_b32_e32 v38, 0xfffe0000, v38
	v_cvt_pk_bf16_f32 v34, v34, v38
	ds_write_b32 v110, v34 offset:11352
	v_bfe_u32 v34, v35, 17, 1
	v_add3_u32 v34, v35, v34, s86
	v_bfe_u32 v35, v39, 17, 1
	v_and_b32_e32 v34, 0xfffe0000, v34
	v_add3_u32 v35, v39, v35, s86
	v_and_b32_e32 v35, 0xfffe0000, v35
	v_cvt_pk_bf16_f32 v34, v34, v35
	ds_write_b32 v110, v34 offset:11480
	v_bfe_u32 v34, v36, 17, 1
	v_add3_u32 v34, v36, v34, s86
	v_bfe_u32 v35, v40, 17, 1
	v_and_b32_e32 v34, 0xfffe0000, v34
	v_add3_u32 v35, v40, v35, s86
	v_and_b32_e32 v35, 0xfffe0000, v35
	v_cvt_pk_bf16_f32 v34, v34, v35
	ds_write_b32 v110, v34 offset:11608
	v_bfe_u32 v34, v37, 17, 1
	v_add3_u32 v34, v37, v34, s86
	v_bfe_u32 v35, v41, 17, 1
	v_and_b32_e32 v34, 0xfffe0000, v34
	v_add3_u32 v35, v41, v35, s86
	v_and_b32_e32 v35, 0xfffe0000, v35
	v_cvt_pk_bf16_f32 v34, v34, v35
	ds_write_b32 v110, v34 offset:11736
	s_waitcnt vmcnt(7)
	v_bfe_u32 v34, v26, 17, 1
	v_add3_u32 v26, v26, v34, s86
	s_waitcnt vmcnt(6)
	v_bfe_u32 v34, v30, 17, 1
	v_and_b32_e32 v26, 0xfffe0000, v26
	v_add3_u32 v30, v30, v34, s86
	v_and_b32_e32 v30, 0xfffe0000, v30
	v_cvt_pk_bf16_f32 v26, v26, v30
	ds_write_b32 v110, v26 offset:12384
	v_bfe_u32 v26, v27, 17, 1
	v_add3_u32 v26, v27, v26, s86
	v_bfe_u32 v27, v31, 17, 1
	v_and_b32_e32 v26, 0xfffe0000, v26
	v_add3_u32 v27, v31, v27, s86
	v_and_b32_e32 v27, 0xfffe0000, v27
	v_cvt_pk_bf16_f32 v26, v26, v27
	ds_write_b32 v110, v26 offset:12512
	v_bfe_u32 v26, v28, 17, 1
	v_add3_u32 v26, v28, v26, s86
	v_bfe_u32 v27, v32, 17, 1
	v_and_b32_e32 v26, 0xfffe0000, v26
	v_add3_u32 v27, v32, v27, s86
	v_and_b32_e32 v27, 0xfffe0000, v27
	v_cvt_pk_bf16_f32 v26, v26, v27
	ds_write_b32 v110, v26 offset:12640
	v_bfe_u32 v26, v29, 17, 1
	v_add3_u32 v26, v29, v26, s86
	v_bfe_u32 v27, v33, 17, 1
	v_and_b32_e32 v26, 0xfffe0000, v26
	v_add3_u32 v27, v33, v27, s86
	v_and_b32_e32 v27, 0xfffe0000, v27
	v_cvt_pk_bf16_f32 v26, v26, v27
	ds_write_b32 v110, v26 offset:12768
	s_waitcnt vmcnt(5)
	v_bfe_u32 v26, v18, 17, 1
	v_add3_u32 v18, v18, v26, s86
	s_waitcnt vmcnt(4)
	v_bfe_u32 v26, v22, 17, 1
	v_and_b32_e32 v18, 0xfffe0000, v18
	v_add3_u32 v22, v22, v26, s86
	v_and_b32_e32 v22, 0xfffe0000, v22
	v_cvt_pk_bf16_f32 v18, v18, v22
	ds_write_b32 v110, v18 offset:13416
	v_bfe_u32 v18, v19, 17, 1
	v_add3_u32 v18, v19, v18, s86
	v_bfe_u32 v19, v23, 17, 1
	v_and_b32_e32 v18, 0xfffe0000, v18
	v_add3_u32 v19, v23, v19, s86
	v_and_b32_e32 v19, 0xfffe0000, v19
	v_cvt_pk_bf16_f32 v18, v18, v19
	ds_write_b32 v110, v18 offset:13544
	v_bfe_u32 v18, v20, 17, 1
	v_add3_u32 v18, v20, v18, s86
	v_bfe_u32 v19, v24, 17, 1
	v_and_b32_e32 v18, 0xfffe0000, v18
	v_add3_u32 v19, v24, v19, s86
	v_and_b32_e32 v19, 0xfffe0000, v19
	v_cvt_pk_bf16_f32 v18, v18, v19
	ds_write_b32 v110, v18 offset:13672
	v_bfe_u32 v18, v21, 17, 1
	v_add3_u32 v18, v21, v18, s86
	v_bfe_u32 v19, v25, 17, 1
	v_and_b32_e32 v18, 0xfffe0000, v18
	v_add3_u32 v19, v25, v19, s86
	v_and_b32_e32 v19, 0xfffe0000, v19
	v_cvt_pk_bf16_f32 v18, v18, v19
	ds_write_b32 v110, v18 offset:13800
	s_waitcnt vmcnt(3)
	v_bfe_u32 v18, v10, 17, 1
	v_add3_u32 v10, v10, v18, s86
	s_waitcnt vmcnt(2)
	v_bfe_u32 v18, v14, 17, 1
	v_and_b32_e32 v10, 0xfffe0000, v10
	v_add3_u32 v14, v14, v18, s86
	v_and_b32_e32 v14, 0xfffe0000, v14
	v_cvt_pk_bf16_f32 v10, v10, v14
	ds_write_b32 v110, v10 offset:14448
	v_bfe_u32 v10, v11, 17, 1
	v_add3_u32 v10, v11, v10, s86
	v_bfe_u32 v11, v15, 17, 1
	v_and_b32_e32 v10, 0xfffe0000, v10
	v_add3_u32 v11, v15, v11, s86
	v_and_b32_e32 v11, 0xfffe0000, v11
	v_cvt_pk_bf16_f32 v10, v10, v11
	ds_write_b32 v110, v10 offset:14576
	v_bfe_u32 v10, v12, 17, 1
	v_add3_u32 v10, v12, v10, s86
	v_bfe_u32 v11, v16, 17, 1
	v_and_b32_e32 v10, 0xfffe0000, v10
	v_add3_u32 v11, v16, v11, s86
	v_and_b32_e32 v11, 0xfffe0000, v11
	v_cvt_pk_bf16_f32 v10, v10, v11
	ds_write_b32 v110, v10 offset:14704
	v_bfe_u32 v10, v13, 17, 1
	v_add3_u32 v10, v13, v10, s86
	v_bfe_u32 v11, v17, 17, 1
	v_and_b32_e32 v10, 0xfffe0000, v10
	v_add3_u32 v11, v17, v11, s86
	v_and_b32_e32 v11, 0xfffe0000, v11
	v_cvt_pk_bf16_f32 v10, v10, v11
	ds_write_b32 v110, v10 offset:14832
	s_waitcnt vmcnt(1)
	v_bfe_u32 v10, v2, 17, 1
	v_add3_u32 v2, v2, v10, s86
	s_waitcnt vmcnt(0)
	v_bfe_u32 v10, v6, 17, 1
	v_and_b32_e32 v2, 0xfffe0000, v2
	v_add3_u32 v6, v6, v10, s86
	v_and_b32_e32 v6, 0xfffe0000, v6
	v_cvt_pk_bf16_f32 v2, v2, v6
	ds_write_b32 v110, v2 offset:15480
	v_bfe_u32 v2, v3, 17, 1
	v_add3_u32 v2, v3, v2, s86
	v_bfe_u32 v3, v7, 17, 1
	v_and_b32_e32 v2, 0xfffe0000, v2
	v_add3_u32 v3, v7, v3, s86
	v_and_b32_e32 v3, 0xfffe0000, v3
	v_cvt_pk_bf16_f32 v2, v2, v3
	ds_write_b32 v110, v2 offset:15608
	v_bfe_u32 v2, v4, 17, 1
	v_add3_u32 v2, v4, v2, s86
	v_bfe_u32 v3, v8, 17, 1
	v_and_b32_e32 v2, 0xfffe0000, v2
	v_add3_u32 v3, v8, v3, s86
	v_and_b32_e32 v3, 0xfffe0000, v3
	v_cvt_pk_bf16_f32 v2, v2, v3
	ds_write_b32 v110, v2 offset:15736
	v_bfe_u32 v2, v5, 17, 1
	v_add3_u32 v2, v5, v2, s86
	v_bfe_u32 v3, v9, 17, 1
	v_and_b32_e32 v2, 0xfffe0000, v2
	v_add3_u32 v3, v9, v3, s86
	v_and_b32_e32 v3, 0xfffe0000, v3
	v_cvt_pk_bf16_f32 v2, v2, v3
	ds_write_b32 v110, v2 offset:15864
	s_waitcnt lgkmcnt(0)
	ds_read2_b32 v[20:21], v146 offset1:8
	ds_read2_b32 v[4:5], v146 offset0:129 offset1:137
	v_add_u32_e32 v30, 0x400, v146
	ds_read2_b32 v[22:23], v30 offset0:2 offset1:10
	ds_read2_b32 v[6:7], v30 offset0:131 offset1:139
	v_add_u32_e32 v32, 0x400, v147
	ds_read2_b32 v[24:25], v147 offset1:8
	ds_read2_b32 v[12:13], v147 offset0:129 offset1:137
	ds_read2_b32 v[26:27], v32 offset0:2 offset1:10
	ds_read2_b32 v[14:15], v32 offset0:131 offset1:139
	v_or_b32_e32 v31, s44, v131
	v_lshl_add_u64 v[2:3], s[40:41], 0, v[132:133]
	s_waitcnt lgkmcnt(6)
	v_mov_b32_e32 v9, v4
	v_or3_b32 v4, v31, v145, s2
	v_or_b32_e32 v33, s44, v144
	v_lshl_add_u64 v[2:3], v[2:3], 0, s[4:5]
	v_lshlrev_b32_e32 v132, 7, v4
	v_or3_b32 v4, v33, v145, s2
	v_mov_b32_e32 v8, v20
	s_waitcnt lgkmcnt(5)
	v_mov_b32_e32 v10, v22
	s_waitcnt lgkmcnt(4)
	v_mov_b32_e32 v11, v6
	v_lshl_add_u64 v[16:17], v[2:3], 0, v[132:133]
	v_lshlrev_b32_e32 v132, 7, v4
	global_store_dwordx4 v[16:17], v[8:11], off
	v_lshl_add_u64 v[16:17], v[2:3], 0, v[132:133]
	v_add_u32_e32 v4, 0x400, v149
	s_waitcnt lgkmcnt(3)
	v_mov_b32_e32 v8, v24
	s_waitcnt lgkmcnt(2)
	v_mov_b32_e32 v9, v12
	s_waitcnt lgkmcnt(1)
	v_mov_b32_e32 v10, v26
	s_waitcnt lgkmcnt(0)
	v_mov_b32_e32 v11, v14
	global_store_dwordx4 v[16:17], v[8:11], off
	ds_read2_b32 v[10:11], v4 offset0:2 offset1:131
	v_or3_b32 v4, v31, v148, s2
	ds_read2_b32 v[8:9], v149 offset1:129
	v_lshlrev_b32_e32 v132, 7, v4
	v_add_u32_e32 v4, 0x400, v150
	ds_read2_b32 v[16:17], v150 offset1:129
	ds_read2_b32 v[18:19], v4 offset0:2 offset1:131
	v_or3_b32 v4, v33, v148, s2
	v_lshl_add_u64 v[28:29], v[2:3], 0, v[132:133]
	v_lshlrev_b32_e32 v132, 7, v4
	s_waitcnt lgkmcnt(2)
	global_store_dwordx4 v[28:29], v[8:11], off
	v_mov_b32_e32 v4, v21
	v_mov_b32_e32 v6, v23
	v_lshl_add_u64 v[8:9], v[2:3], 0, v[132:133]
	s_waitcnt lgkmcnt(0)
	global_store_dwordx4 v[8:9], v[16:19], off
	v_or3_b32 v8, v31, v151, s2
	v_lshlrev_b32_e32 v132, 7, v8
	v_lshl_add_u64 v[8:9], v[2:3], 0, v[132:133]
	global_store_dwordx4 v[8:9], v[4:7], off
	v_mov_b32_e32 v12, v25
	v_mov_b32_e32 v14, v27
	v_or3_b32 v4, v33, v151, s2
	v_add_u32_e32 v6, 0x400, v153
	v_lshlrev_b32_e32 v132, 7, v4
	ds_read2_b32 v[4:5], v153 offset1:129
	ds_read2_b32 v[6:7], v6 offset0:2 offset1:131
	v_lshl_add_u64 v[8:9], v[2:3], 0, v[132:133]
	global_store_dwordx4 v[8:9], v[12:15], off
	v_or3_b32 v8, v31, v152, s2
	v_lshlrev_b32_e32 v132, 7, v8
	v_lshl_add_u64 v[8:9], v[2:3], 0, v[132:133]
	s_waitcnt lgkmcnt(0)
	global_store_dwordx4 v[8:9], v[4:7], off
	ds_read2_b32 v[4:5], v154 offset1:129
	v_or3_b32 v8, v33, v152, s2
	v_add_u32_e32 v6, 0x400, v154
	ds_read2_b32 v[6:7], v6 offset0:2 offset1:131
	v_lshlrev_b32_e32 v132, 7, v8
	v_lshl_add_u64 v[12:13], v[2:3], 0, v[132:133]
	ds_read2_b32 v[20:21], v146 offset0:16 offset1:24
	ds_read2_b32 v[8:9], v146 offset0:145 offset1:153
	ds_read2_b32 v[22:23], v30 offset0:18 offset1:26
	ds_read2_b32 v[10:11], v30 offset0:147 offset1:155
	s_mov_b64 s[4:5], 0
	s_waitcnt lgkmcnt(4)
	global_store_dwordx4 v[12:13], v[4:7], off
	ds_read2_b32 v[24:25], v147 offset0:16 offset1:24
	ds_read2_b32 v[12:13], v147 offset0:145 offset1:153
	ds_read2_b32 v[26:27], v32 offset0:18 offset1:26
	ds_read2_b32 v[14:15], v32 offset0:147 offset1:155
	s_waitcnt lgkmcnt(6)
	v_mov_b32_e32 v5, v8
	v_or3_b32 v8, v31, v155, s2
	v_lshlrev_b32_e32 v132, 7, v8
	v_or3_b32 v8, v33, v155, s2
	v_mov_b32_e32 v4, v20
	s_waitcnt lgkmcnt(5)
	v_mov_b32_e32 v6, v22
	s_waitcnt lgkmcnt(4)
	v_mov_b32_e32 v7, v10
	v_lshl_add_u64 v[16:17], v[2:3], 0, v[132:133]
	v_lshlrev_b32_e32 v132, 7, v8
	global_store_dwordx4 v[16:17], v[4:7], off
	v_lshl_add_u64 v[16:17], v[2:3], 0, v[132:133]
	v_or3_b32 v8, v31, v158, s2
	s_waitcnt lgkmcnt(3)
	v_mov_b32_e32 v4, v24
	s_waitcnt lgkmcnt(2)
	v_mov_b32_e32 v5, v12
	s_waitcnt lgkmcnt(1)
	v_mov_b32_e32 v6, v26
	s_waitcnt lgkmcnt(0)
	v_mov_b32_e32 v7, v14
	global_store_dwordx4 v[16:17], v[4:7], off
	ds_read2_b32 v[4:5], v159 offset1:129
	v_lshlrev_b32_e32 v132, 7, v8
	v_add_u32_e32 v6, 0x400, v159
	ds_read2_b32 v[6:7], v6 offset0:2 offset1:131
	v_add_u32_e32 v8, 0x400, v160
	ds_read2_b32 v[16:17], v160 offset1:129
	ds_read2_b32 v[18:19], v8 offset0:2 offset1:131
	v_lshl_add_u64 v[28:29], v[2:3], 0, v[132:133]
	s_waitcnt lgkmcnt(2)
	global_store_dwordx4 v[28:29], v[4:7], off
	v_mov_b32_e32 v8, v21
	v_mov_b32_e32 v10, v23
	v_or3_b32 v4, v33, v158, s2
	v_lshlrev_b32_e32 v132, 7, v4
	v_lshl_add_u64 v[4:5], v[2:3], 0, v[132:133]
	s_waitcnt lgkmcnt(0)
	global_store_dwordx4 v[4:5], v[16:19], off
	v_or3_b32 v4, v31, v161, s2
	v_lshlrev_b32_e32 v132, 7, v4
	v_lshl_add_u64 v[4:5], v[2:3], 0, v[132:133]
	global_store_dwordx4 v[4:5], v[8:11], off
	v_or3_b32 v4, v33, v161, s2
	v_lshlrev_b32_e32 v132, 7, v4
	v_mov_b32_e32 v12, v25
	v_mov_b32_e32 v14, v27
	v_lshl_add_u64 v[4:5], v[2:3], 0, v[132:133]
	v_add_u32_e32 v6, 0x400, v163
	global_store_dwordx4 v[4:5], v[12:15], off
	ds_read2_b32 v[4:5], v163 offset1:129
	ds_read2_b32 v[6:7], v6 offset0:2 offset1:131
	v_or3_b32 v8, v31, v162, s2
	v_add_u32_e32 v10, 0x400, v164
	v_lshlrev_b32_e32 v132, 7, v8
	ds_read2_b32 v[8:9], v164 offset1:129
	ds_read2_b32 v[10:11], v10 offset0:2 offset1:131
	v_lshl_add_u64 v[12:13], v[2:3], 0, v[132:133]
	s_waitcnt lgkmcnt(2)
	global_store_dwordx4 v[12:13], v[4:7], off
	s_nop 1
	v_or3_b32 v4, v33, v162, s2
	v_lshlrev_b32_e32 v132, 7, v4
	v_lshl_add_u64 v[2:3], v[2:3], 0, v[132:133]
	s_waitcnt lgkmcnt(0)
	global_store_dwordx4 v[2:3], v[8:11], off
	s_waitcnt lgkmcnt(0)

.Lwin_all:
	v_writelane_b32 v242, s0, 0
	s_nop 1
	v_writelane_b32 v242, s1, 1
	s_nop 1
	v_writelane_b32 v242, s2, 2
	s_nop 1
	v_writelane_b32 v242, s3, 3
	s_nop 1
	v_writelane_b32 v242, s4, 4
	s_nop 1
	v_writelane_b32 v242, s5, 5
	s_nop 1
	v_writelane_b32 v242, s6, 6
	s_nop 1
	v_writelane_b32 v242, s7, 7
	s_nop 1
	v_writelane_b32 v242, s8, 8
	s_nop 1
	v_writelane_b32 v242, s9, 9
	s_nop 1
	v_writelane_b32 v242, s10, 10
	s_nop 1
	v_writelane_b32 v242, s11, 11
	s_nop 1
	v_writelane_b32 v242, s12, 12
	s_nop 1
	v_writelane_b32 v242, s13, 13
	s_nop 1
	v_writelane_b32 v242, s14, 14
	s_nop 1
	v_writelane_b32 v242, s15, 15
	s_nop 1
	v_writelane_b32 v242, s16, 16
	s_nop 1
	v_writelane_b32 v242, s17, 17
	s_nop 1
	v_writelane_b32 v242, s18, 18
	s_nop 1
	v_writelane_b32 v242, s19, 19
	s_nop 1
	v_writelane_b32 v242, s20, 20
	s_nop 1
	v_writelane_b32 v242, s21, 21
	s_nop 1
	v_writelane_b32 v242, s22, 22
	s_nop 1
	v_writelane_b32 v242, s23, 23
	s_nop 1
	v_writelane_b32 v242, s24, 24
	s_nop 1
	v_writelane_b32 v242, s25, 25
	s_nop 1
	v_writelane_b32 v242, s26, 26
	s_nop 1
	v_writelane_b32 v242, s27, 27
	s_nop 1
	v_writelane_b32 v242, s28, 28
	s_nop 1
	v_writelane_b32 v242, s29, 29
	s_nop 1
	v_writelane_b32 v242, s30, 30
	s_nop 1
	v_writelane_b32 v242, s31, 31
	s_nop 1
	v_writelane_b32 v242, s32, 32
	s_nop 1
	v_writelane_b32 v242, s33, 33
	s_nop 1
	v_writelane_b32 v242, s34, 34
	s_nop 1
	v_writelane_b32 v242, s35, 35
	s_nop 1
	v_writelane_b32 v242, s36, 36
	s_nop 1
	v_writelane_b32 v242, s37, 37
	s_nop 1
	v_writelane_b32 v242, s38, 38
	s_nop 1
	v_writelane_b32 v242, s39, 39
	s_nop 1
	v_writelane_b32 v242, s40, 40
	s_nop 1
	v_writelane_b32 v242, s41, 41
	s_nop 1
	v_writelane_b32 v242, s42, 42
	s_nop 1
	v_writelane_b32 v242, s43, 43
	s_nop 1
	v_writelane_b32 v242, s44, 44
	s_nop 1
	v_writelane_b32 v242, s45, 45
	s_nop 1
	v_writelane_b32 v242, s46, 46
	s_nop 1
	v_writelane_b32 v242, s47, 47
	s_nop 1
	v_writelane_b32 v242, s48, 48
	s_nop 1
	v_writelane_b32 v242, s49, 49
	s_nop 1
	v_writelane_b32 v242, s50, 50
	s_nop 1
	v_writelane_b32 v242, s51, 51
	s_nop 1
	v_writelane_b32 v242, s52, 52
	s_nop 1
	v_writelane_b32 v242, s53, 53
	s_nop 1
	v_writelane_b32 v242, s54, 54
	s_nop 1
	v_writelane_b32 v242, s55, 55
	s_nop 1
	v_writelane_b32 v242, s56, 56
	s_nop 1
	v_writelane_b32 v242, s57, 57
	s_nop 1
	v_writelane_b32 v242, s58, 58
	s_nop 1
	v_writelane_b32 v242, s59, 59
	s_nop 1
	v_writelane_b32 v242, s60, 60
	s_nop 1
	v_writelane_b32 v242, s61, 61
	s_nop 1
	v_writelane_b32 v242, s62, 62
	s_nop 1
	v_writelane_b32 v242, s63, 63
	s_nop 1
	v_writelane_b32 v243, s64, 0
	s_nop 1
	v_writelane_b32 v243, s65, 1
	s_nop 1
	v_writelane_b32 v243, s66, 2
	s_nop 1
	v_writelane_b32 v243, s67, 3
	s_nop 1
	v_writelane_b32 v243, s68, 4
	s_nop 1
	v_writelane_b32 v243, s69, 5
	s_nop 1
	v_writelane_b32 v243, s70, 6
	s_nop 1
	v_writelane_b32 v243, s71, 7
	s_nop 1
	v_writelane_b32 v243, s72, 8
	s_nop 1
	v_writelane_b32 v243, s73, 9
	s_nop 1
	v_writelane_b32 v243, s74, 10
	s_nop 1
	v_writelane_b32 v243, s75, 11
	s_nop 1
	v_writelane_b32 v243, s76, 12
	s_nop 1
	v_writelane_b32 v243, s77, 13
	s_nop 1
	v_writelane_b32 v243, s78, 14
	s_nop 1
	v_writelane_b32 v243, s79, 15
	s_nop 1
	v_writelane_b32 v243, s80, 16
	s_nop 1
	v_writelane_b32 v243, s81, 17
	s_nop 1
	v_writelane_b32 v243, s82, 18
	s_nop 1
	v_writelane_b32 v243, s83, 19
	s_nop 1
	v_writelane_b32 v243, s84, 20
	s_nop 1
	v_writelane_b32 v243, s85, 21
	s_nop 1
	v_writelane_b32 v243, s86, 22
	s_nop 1
	v_writelane_b32 v243, s87, 23
	s_nop 1
	v_writelane_b32 v243, s88, 24
	s_nop 1
	v_writelane_b32 v243, s89, 25
	s_nop 1
	v_writelane_b32 v243, s90, 26
	s_nop 1
	v_writelane_b32 v243, s91, 27
	s_nop 1
	v_writelane_b32 v243, s92, 28
	s_nop 1
	v_writelane_b32 v243, s93, 29
	s_nop 1
	v_writelane_b32 v243, s94, 30
	s_nop 1
	v_writelane_b32 v243, s95, 31
	s_nop 1
	v_writelane_b32 v243, s96, 32
	s_nop 1
	v_writelane_b32 v243, s97, 33
	s_nop 1
	v_writelane_b32 v243, s98, 34
	s_nop 1
	v_writelane_b32 v243, s99, 35
	s_nop 1
	v_writelane_b32 v243, vcc_lo, 36
	s_nop 1
	v_writelane_b32 v243, vcc_hi, 37
	s_mov_b64 s[0:1], exec
	s_nop 1
	v_writelane_b32 v243, s0, 38
	s_nop 1
	v_writelane_b32 v243, s1, 39
	s_mov_b64 exec, -1
	v_mov_b32_e32 v244, v241
	v_mov_b32_e32 v245, v4
	v_mov_b32_e32 v246, v33
	s_cmp_gt_u32 s70, 2
	s_cselect_b32 s4, 1, 0
	s_nop 0
	v_writelane_b32 v247, s4, 3
	s_movk_i32 s4, 0x1000
	s_nop 0
	v_writelane_b32 v247, s4, 0
	s_nop 1
	v_writelane_b32 v247, s4, 5
	s_movk_i32 s4, 0x7fff
	s_nop 0
	v_writelane_b32 v247, s4, 9
	s_nop 1
	v_writelane_b32 v247, s4, 8
	s_movk_i32 s4, 0xb00
	s_nop 0
	v_writelane_b32 v247, s4, 1
	s_movk_i32 s4, 0x1400
	s_nop 0
	v_writelane_b32 v247, s4, 2
	s_lshl_b32 s4, s66, 3
	s_cmpk_eq_i32 s66, 0x100
	s_cselect_b32 s4, 0x400, s4
	s_cselect_b32 s3, 0x400, 0
	s_nop 0
	v_writelane_b32 v247, s4, 4
	s_mov_b32 s4, 1
	s_nop 0
	v_writelane_b32 v247, s4, 6
	s_load_dwordx8 s[8:15], s[30:31], 0x0
	s_load_dwordx4 s[24:27], s[30:31], 0x20
	s_load_dwordx2 s[6:7], s[30:31], 0x30
	s_load_dwordx4 s[64:67], s[30:31], 0xb0
	v_readfirstlane_b32 s2, v156
	s_lshl_b32 s4, s74, 3
	s_lshr_b32 s100, s2, 6
	s_add_i32 s100, s100, s4
	s_sub_i32 s100, s100, s3
	s_waitcnt lgkmcnt(0)
	s_branch .Lconv_pre
